# baseline (speedup 1.0000x reference)
.LBB0_908:
	s_cmp_gt_u32 s61, 5
	s_mov_b64 s[0:1], -1
	s_cbranch_scc0 .LBB0_920
	v_readlane_b32 s0, v251, 15
	s_sub_i32 s5, s51, 64
	s_add_i32 s58, s50, 0xffffff40
	v_readlane_b32 s1, v251, 16
	s_and_b64 s[0:1], s[0:1], exec
	s_cselect_b32 s0, s58, s5
	v_readlane_b32 s1, v254, 36
	s_add_i32 s5, s0, s1
	s_mov_b64 s[0:1], 0

; __device__ __forceinline__ void hgrn_phase(const Params& P, char* shm, int lbid) {
;     ...
;     for (int c = 0; c < NCH; ++c) {
; #pragma unroll
;       for (int vt = 0; vt < 8; ++vt) {
;         u32x2 pk;
;         pk.x = pack2(Sacc[vt][0], Sacc[vt][1]);
;         pk.y = pack2(Sacc[vt][2], Sacc[vt][3]);
;         *(u32x2*)(sb + (vt * 16 + fr) * QSTR + (16 * w + quad * 4) * 2) = pk;
;       }
;       if (c + 1 < NCH) HG_PRODUCE(c + 1);
;       if (c + 2 < NCH) HG_ISSUE(c + 2);
.LBB0_922:
	v_add_u32_e32 v200, s5, v114
	v_ashrrev_i32_e32 v201, 31, v200
	v_lshlrev_b64 v[200:201], 9, v[200:201]
	v_lshl_add_u64 v[200:201], v[200:201], 0, v[72:73]
	v_lshl_add_u64 v[202:203], v[200:201], 2, s[34:35]
	v_lshl_add_u64 v[200:201], v[200:201], 1, s[62:63]
	global_load_dword v214, v[202:203], off
	global_load_ushort v206, v[200:201], off
	v_add_u32_e32 v200, s5, v94
	v_ashrrev_i32_e32 v201, 31, v200
	v_lshlrev_b64 v[200:201], 9, v[200:201]
	v_lshl_add_u64 v[200:201], v[200:201], 0, v[72:73]
	v_lshl_add_u64 v[202:203], v[200:201], 2, s[34:35]
	v_lshl_add_u64 v[200:201], v[200:201], 1, s[62:63]
	global_load_dword v215, v[202:203], off
	global_load_ushort v207, v[200:201], off
	v_add_u32_e32 v200, s5, v95
	v_ashrrev_i32_e32 v201, 31, v200
	v_lshlrev_b64 v[200:201], 9, v[200:201]
	v_lshl_add_u64 v[200:201], v[200:201], 0, v[72:73]
	v_lshl_add_u64 v[202:203], v[200:201], 2, s[34:35]
	v_lshl_add_u64 v[200:201], v[200:201], 1, s[62:63]
	global_load_dword v216, v[202:203], off
	global_load_ushort v208, v[200:201], off
	v_add_u32_e32 v200, s5, v96
	v_ashrrev_i32_e32 v201, 31, v200
	v_lshlrev_b64 v[200:201], 9, v[200:201]
	v_lshl_add_u64 v[200:201], v[200:201], 0, v[72:73]
	v_lshl_add_u64 v[202:203], v[200:201], 2, s[34:35]
	v_lshl_add_u64 v[200:201], v[200:201], 1, s[62:63]
	global_load_dword v217, v[202:203], off
	global_load_ushort v209, v[200:201], off
	v_add_u32_e32 v200, s5, v97
	v_ashrrev_i32_e32 v201, 31, v200
	v_lshlrev_b64 v[200:201], 9, v[200:201]
	v_lshl_add_u64 v[200:201], v[200:201], 0, v[72:73]
	v_lshl_add_u64 v[202:203], v[200:201], 2, s[34:35]
	v_lshl_add_u64 v[200:201], v[200:201], 1, s[62:63]
	global_load_dword v218, v[202:203], off
	global_load_ushort v210, v[200:201], off
	v_add_u32_e32 v200, s5, v99
	v_ashrrev_i32_e32 v201, 31, v200
	v_lshlrev_b64 v[200:201], 9, v[200:201]
	v_lshl_add_u64 v[200:201], v[200:201], 0, v[72:73]
	v_lshl_add_u64 v[202:203], v[200:201], 2, s[34:35]
	v_lshl_add_u64 v[200:201], v[200:201], 1, s[62:63]
	global_load_dword v219, v[202:203], off
	global_load_ushort v211, v[200:201], off
	v_add_u32_e32 v200, s5, v101
	v_ashrrev_i32_e32 v201, 31, v200
	v_lshlrev_b64 v[200:201], 9, v[200:201]
	v_lshl_add_u64 v[200:201], v[200:201], 0, v[72:73]
	v_lshl_add_u64 v[202:203], v[200:201], 2, s[34:35]
	v_lshl_add_u64 v[200:201], v[200:201], 1, s[62:63]
	global_load_dword v226, v[202:203], off
	global_load_ushort v212, v[200:201], off
	v_add_u32_e32 v200, s5, v103
	v_ashrrev_i32_e32 v201, 31, v200
	v_lshlrev_b64 v[200:201], 9, v[200:201]
	v_lshl_add_u64 v[200:201], v[200:201], 0, v[72:73]
	v_lshl_add_u64 v[202:203], v[200:201], 2, s[34:35]
	v_lshl_add_u64 v[200:201], v[200:201], 1, s[62:63]
	global_load_dword v227, v[202:203], off
	global_load_ushort v213, v[200:201], off
	v_add_u32_e32 v200, s5, v105
	v_ashrrev_i32_e32 v201, 31, v200
	v_lshlrev_b64 v[200:201], 10, v[200:201]
	v_lshl_add_u64 v[200:201], v[80:81], 0, v[200:201]
	global_load_dwordx4 v[220:223], v[200:201], off
	v_cvt_pk_bf16_f32 v4, v4, v5
	v_cvt_pk_bf16_f32 v5, v6, v7
	ds_write_b64 v91, v[4:5]
	v_cvt_pk_bf16_f32 v4, v12, v13
	v_cvt_pk_bf16_f32 v5, v14, v15
	ds_write_b64 v91, v[4:5] offset:4352
	v_cvt_pk_bf16_f32 v5, v18, v19
	v_mul_f32_e32 v18, v84, v85
	v_cvt_pk_bf16_f32 v4, v16, v17
	v_mul_f32_e32 v17, v78, v18
	v_mul_f32_e32 v16, v79, v17
	ds_write_b64 v91, v[4:5] offset:8704
	v_cvt_pk_bf16_f32 v4, v20, v21
	v_cvt_pk_bf16_f32 v5, v22, v23
	v_mul_f32_e32 v15, v82, v16
	ds_write_b64 v91, v[4:5] offset:13056
	v_cvt_pk_bf16_f32 v4, v24, v25
	v_cvt_pk_bf16_f32 v5, v26, v27
	v_mul_f32_e32 v14, v83, v15
	ds_write_b64 v91, v[4:5] offset:17408
	v_cvt_pk_bf16_f32 v4, v28, v29
	v_cvt_pk_bf16_f32 v5, v30, v31
	v_mul_f32_e32 v13, v76, v14
	ds_write_b64 v91, v[4:5] offset:21760
	v_cvt_pk_bf16_f32 v4, v32, v33
	v_cvt_pk_bf16_f32 v5, v34, v35
	v_mul_f32_e32 v12, v77, v13
	ds_write_b64 v91, v[4:5] offset:26112
	ds_bpermute_b32 v4, v102, v12
	ds_bpermute_b32 v5, v109, v12
	ds_bpermute_b32 v6, v110, v12
	ds_bpermute_b32 v7, v111, v12
	v_cvt_pk_bf16_f32 v8, v8, v9
	v_cvt_pk_bf16_f32 v9, v10, v11
	ds_write_b64 v91, v[8:9] offset:30464
	v_mov_b32_e32 v8, 1.0
	s_and_saveexec_b64 s[0:1], s[24:25]
	s_cbranch_execz .LBB0_916
	v_cmp_lt_i32_e32 vcc, 1, v93
	s_waitcnt lgkmcnt(4)
	v_mov_b32_e32 v8, v4
	s_and_saveexec_b64 s[4:5], vcc
	s_cbranch_execz .LBB0_915
	s_mov_b64 s[26:27], s[90:91]
	v_cmp_ne_u32_e32 vcc, 2, v93
	s_and_saveexec_b64 s[58:59], vcc
	s_xor_b64 vcc, exec, s[58:59]
	s_cbranch_execz .LBB0_912
	s_waitcnt lgkmcnt(3)
	v_mul_f32_e32 v8, v4, v5
	s_waitcnt lgkmcnt(2)
	v_mul_f32_e32 v8, v8, v6

; __device__ __forceinline__ void hgrn_phase(const Params& P, char* shm, int lbid) {
;     ...
;       __syncthreads();
;       const char* pb = shm + (c & 1) * PB;
;       {
;         const bf16x8 a = *(const bf16x8*)(pb + PB_KT + (16 * w + fr) * TSTR + quad * 16);
;         const float4 gl = *(const float4*)(pb + PB_GL + (16 * w + quad * 4) * 4);
; #pragma unroll
;         for (int vt = 0; vt < 8; ++vt) {
;           const bf16x8 bv = *(const bf16x8*)(pb + PB_VT + (vt * 16 + fr) * TSTR + quad * 16);
;           f32x4 t = __builtin_amdgcn_mfma_f32_16x16x32_bf16(a, bv, Sacc[vt], 0, 0, 0);
;           t[0] *= gl.x; t[1] *= gl.y; t[2] *= gl.z; t[3] *= gl.w;
;           Sacc[vt] = t;
;         }
;       }
;       {
;         const int tt = w >> 2, vt0 = (w & 3) * 2;
;         bf16x8 qf[4];
; #pragma unroll
;         for (int ks = 0; ks < 4; ++ks) qf[ks] = *(const bf16x8*)(pb + PB_Q + (tt * 16 + fr) * QSTR + (ks * 32 + quad * 8) * 2);
;         f32x4 AT[2];
; #pragma unroll
;         for (int st = 0; st < 2; ++st) {
;           f32x4 acc = f32x4{0.f, 0.f, 0.f, 0.f};
; #pragma unroll
;           for (int ks = 0; ks < 4; ++ks) {
;             const bf16x8 kf = *(const bf16x8*)(pb + PB_K + (st * 16 + fr) * QSTR + (ks * 32 + quad * 8) * 2);
;             acc = __builtin_amdgcn_mfma_f32_16x16x32_bf16(kf, qf[ks], acc, 0, 0, 0);
;           }
;           const int tpos = tt * 16 + fr;
; #pragma unroll
;           for (int jj = 0; jj < 4; ++jj)
;             if (st * 16 + quad * 4 + jj > tpos) acc[jj] = 0.0f;
;           AT[st] = acc;
;         }
.LBB0_918:
	s_or_b64 exec, exec, s[0:1]
	s_waitcnt lgkmcnt(14)
	v_add3_u32 v4, s5, v106, v107
	ds_write_b16 v4, v0 offset:27648
	ds_write_b16_d16_hi v4, v0 offset:27728
	ds_write_b16 v4, v1 offset:27808
	ds_write_b16_d16_hi v4, v1 offset:27888
	ds_write_b16 v4, v2 offset:27968
	ds_write_b16_d16_hi v4, v2 offset:28048
	ds_write_b16 v4, v3 offset:28128
	ds_write_b16_d16_hi v4, v3 offset:28208
	s_bitcmp1_b32 s61, 0
	s_cselect_b32 s74, 0x9600, 0
	v_add_u32_e32 v4, s74, v74
	v_add_u32_e32 v126, v4, v92
	s_waitcnt lgkmcnt(0)
	s_barrier
	ds_read_b128 v[120:123], v126 offset:17408
	v_or_b32_e32 v124, s74, v92
	v_add_u32_e32 v125, v124, v117
	ds_read_b128 v[4:7], v125 offset:27648
	ds_read_b128 v[8:11], v125 offset:28928
	s_waitcnt lgkmcnt(0)
	v_mfma_f32_16x16x32_bf16 v[12:15], v[120:123], v[8:11], v[40:43]
	ds_read_b128 v[8:11], v125 offset:30208
	ds_read_b128 v[28:31], v125 offset:34048
	ds_read_b128 v[32:35], v125 offset:35328
	s_waitcnt lgkmcnt(2)
	v_mfma_f32_16x16x32_bf16 v[16:19], v[120:123], v[8:11], v[44:47]
	ds_read_b128 v[8:11], v125 offset:31488
	s_cmp_gt_u32 s61, 7
	s_mov_b64 s[0:1], -1
	v_mfma_f32_16x16x32_bf16 v[4:7], v[120:123], v[4:7], v[36:39]
	s_waitcnt lgkmcnt(0)
	v_mfma_f32_16x16x32_bf16 v[20:23], v[120:123], v[8:11], v[48:51]
	ds_read_b128 v[8:11], v125 offset:32768
	ds_read_b128 v[36:39], v125 offset:36608
	v_add_u32_e32 v125, v124, v100
	ds_read_b128 v[40:43], v125 offset:8704
	v_add_u32_e32 v124, v124, v112
	ds_read_b128 v[48:51], v124
	v_mfma_f32_16x16x32_bf16 v[28:31], v[120:123], v[28:31], v[56:59]
	s_waitcnt lgkmcnt(2)
	v_mfma_f32_16x16x32_bf16 v[56:59], v[120:123], v[36:39], v[64:67]
	ds_read_b128 v[36:39], v125 offset:8768
	ds_read_b128 v[44:47], v124 offset:64
	v_mfma_f32_16x16x32_bf16 v[8:11], v[120:123], v[8:11], v[52:55]
	s_waitcnt lgkmcnt(2)
	v_mfma_f32_16x16x32_bf16 v[52:55], v[40:43], v[48:51], 0
	v_mfma_f32_16x16x32_bf16 v[32:35], v[120:123], v[32:35], v[60:63]
	s_nop 2
	ds_read_b128 v[60:63], v125 offset:8832
	ds_read_b128 v[40:43], v124 offset:128
	ds_read_b128 v[64:67], v125 offset:13120
	ds_read_b128 v[120:123], v125 offset:13248
	s_waitcnt lgkmcnt(4)
	v_mfma_f32_16x16x32_bf16 v[36:39], v[36:39], v[44:47], v[52:55]
	s_nop 2
	ds_read_b128 v[52:55], v125 offset:8896
	s_waitcnt lgkmcnt(3)
	v_mfma_f32_16x16x32_bf16 v[60:63], v[60:63], v[40:43], v[36:39]
	s_nop 2
	ds_read_b128 v[36:39], v124 offset:192
	s_waitcnt lgkmcnt(0)
	v_mfma_f32_16x16x32_bf16 v[52:55], v[52:55], v[36:39], v[60:63]
	s_nop 2
	ds_read_b128 v[60:63], v125 offset:13056
	s_waitcnt lgkmcnt(0)
	v_mfma_f32_16x16x32_bf16 v[60:63], v[60:63], v[48:51], 0
	v_mfma_f32_16x16x32_bf16 v[60:63], v[64:67], v[44:47], v[60:63]
	ds_read_b128 v[64:67], v125 offset:13184
	s_waitcnt lgkmcnt(0)
	v_mfma_f32_16x16x32_bf16 v[60:63], v[64:67], v[40:43], v[60:63]
	v_add_u32_e32 v64, s74, v113
	ds_read_b128 v[64:67], v64 offset:37888
	v_mfma_f32_16x16x32_bf16 v[60:63], v[120:123], v[36:39], v[60:63]
	s_cbranch_scc0 .LBB0_924
	v_readlane_b32 s0, v251, 15
	s_add_i32 s5, s50, 0xffffff00
	v_readlane_b32 s1, v251, 16
	s_and_b64 s[0:1], s[0:1], exec
	s_cselect_b32 s0, s5, s51
	v_readlane_b32 s1, v254, 36
	s_add_i32 s5, s0, s1
	s_mov_b64 s[0:1], 0

; __device__ __forceinline__ void hgrn_phase(const Params& P, char* shm, int lbid) {
;     ...
;           f32x4 t = __builtin_amdgcn_mfma_f32_16x16x32_bf16(a, bv, Sacc[vt], 0, 0, 0);
;           t[0] *= gl.x; t[1] *= gl.y; t[2] *= gl.z; t[3] *= gl.w;
;           Sacc[vt] = t;
;         }
;       }
;       {
;         const int tt = w >> 2, vt0 = (w & 3) * 2;
;         bf16x8 qf[4];
; #pragma unroll
;         for (int ks = 0; ks < 4; ++ks) qf[ks] = *(const bf16x8*)(pb + PB_Q + (tt * 16 + fr) * QSTR + (ks * 32 + quad * 8) * 2);
;         f32x4 AT[2];
; #pragma unroll
;         for (int st = 0; st < 2; ++st) {
;           f32x4 acc = f32x4{0.f, 0.f, 0.f, 0.f};
; #pragma unroll
;           for (int ks = 0; ks < 4; ++ks) {
;             const bf16x8 kf = *(const bf16x8*)(pb + PB_K + (st * 16 + fr) * QSTR + (ks * 32 + quad * 8) * 2);
;             acc = __builtin_amdgcn_mfma_f32_16x16x32_bf16(kf, qf[ks], acc, 0, 0, 0);
;           }
;           const int tpos = tt * 16 + fr;
; #pragma unroll
;           for (int jj = 0; jj < 4; ++jj)
;             if (st * 16 + quad * 4 + jj > tpos) acc[jj] = 0.0f;
;           AT[st] = acc;
;         }
;         u32x4 ap;
;         ap.x = pack2(AT[0][0], AT[0][1]); ap.y = pack2(AT[0][2], AT[0][3]);
;         ap.z = pack2(AT[1][0], AT[1][1]); ap.w = pack2(AT[1][2], AT[1][3]);
;         const int r0 = HG_R0(c);
; #pragma unroll
;         for (int e = 0; e < 2; ++e) {
;           const int vt = vt0 + e;
;           f32x4 O = f32x4{0.f, 0.f, 0.f, 0.f};
; #pragma unroll
;           for (int ks = 0; ks < 4; ++ks) {
;             const bf16x8 sf = *(const bf16x8*)(sb + (vt * 16 + fr) * QSTR + (ks * 32 + quad * 8) * 2);
;             O = __builtin_amdgcn_mfma_f32_16x16x32_bf16(qf[ks], sf, O, 0, 0, 0);
;           }
;           const char* vp = pb + PB_VT + (vt * 16 + fr) * TSTR + quad * 8;
;           const u32x2 lo = *(const u32x2*)vp, hi = *(const u32x2*)(vp + 32);
;           u32x4 bp; bp.x = lo.x; bp.y = lo.y; bp.z = hi.x; bp.w = hi.y;
;           O = __builtin_amdgcn_mfma_f32_16x16x32_bf16(__builtin_bit_cast(bf16x8, ap), __builtin_bit_cast(bf16x8, bp), O, 0, 0, 0);
; #pragma unroll
;           for (int jj = 0; jj < 4; ++jj)
;             Oo[(size_t)(r0 + sgn * (tt * 16 + quad * 4 + jj)) * 512 + h * 128 + vt * 16 + fr] = O[jj];
;         }
;       }
;       __syncthreads();
.LBB0_926:
	s_nop 0
	s_nop 0
	s_nop 0
	s_nop 0
	s_waitcnt lgkmcnt(0)
	v_pk_mul_f32 v[24:25], v[64:65], v[8:9]
	v_pk_mul_f32 v[8:9], v[64:65], v[56:57]
	v_mov_b32_e32 v56, s75
	v_cndmask_b32_e64 v56, v52, v56, s[16:17]
	v_cndmask_b32_e64 v56, v56, v52, s[14:15]
	v_mov_b32_e32 v52, s75
	s_nop 0
	s_nop 0
	s_nop 0
	s_nop 0
	v_pk_mul_f32 v[26:27], v[66:67], v[10:11]
	v_pk_mul_f32 v[10:11], v[66:67], v[58:59]
	v_cndmask_b32_e64 v53, 0, v53, s[14:15]
	v_cndmask_b32_e64 v54, v54, 0, s[18:19]
	v_cndmask_b32_e64 v55, v55, 0, s[20:21]
	v_cndmask_b32_e64 v57, v60, v52, s[6:7]
	v_cndmask_b32_e64 v58, v61, 0, s[8:9]
	v_cndmask_b32_e64 v59, v62, 0, s[10:11]
	v_cndmask_b32_e64 v60, v63, 0, s[12:13]
	v_cvt_pk_bf16_f32 v52, v56, v53
	v_cvt_pk_bf16_f32 v53, v54, v55
	v_cvt_pk_bf16_f32 v54, v57, v58
	v_cvt_pk_bf16_f32 v55, v59, v60
	ds_read_b128 v[56:59], v75
	ds_read_b128 v[60:63], v75 offset:64
	s_waitcnt lgkmcnt(1)
	v_mfma_f32_16x16x32_bf16 v[56:59], v[48:51], v[56:59], 0
	s_nop 0
	s_nop 0
	s_nop 0
	s_nop 0
	v_add3_u32 v127, s74, v69, v90
	s_waitcnt lgkmcnt(0)
	v_mfma_f32_16x16x32_bf16 v[56:59], v[44:47], v[60:63], v[56:59]
	ds_read_b128 v[60:63], v75 offset:128
	v_pk_mul_f32 v[4:5], v[64:65], v[4:5]
	v_pk_mul_f32 v[12:13], v[64:65], v[12:13]
	s_waitcnt lgkmcnt(0)
	v_mfma_f32_16x16x32_bf16 v[56:59], v[40:43], v[60:63], v[56:59]
	ds_read_b128 v[60:63], v75 offset:192
	v_pk_mul_f32 v[16:17], v[64:65], v[16:17]
	v_pk_mul_f32 v[20:21], v[64:65], v[20:21]
	s_waitcnt lgkmcnt(0)
	v_mfma_f32_16x16x32_bf16 v[56:59], v[36:39], v[60:63], v[56:59]
	v_add_u32_e32 v60, 0x6800, v127
	ds_read2_b64 v[60:63], v60 offset0:128 offset1:132
	v_pk_mul_f32 v[28:29], v[64:65], v[28:29]
	s_waitcnt lgkmcnt(0)
	v_mfma_f32_16x16x32_bf16 v[56:59], v[52:55], v[60:63], v[56:59]
	v_add_u32_e32 v60, s5, v89
	v_ashrrev_i32_e32 v61, 31, v60
	v_add_u32_e32 v62, s5, v88
	v_lshlrev_b64 v[60:61], 11, v[60:61]
	v_ashrrev_i32_e32 v63, 31, v62
	v_lshl_add_u64 v[60:61], v[70:71], 0, v[60:61]
	v_lshlrev_b64 v[62:63], 11, v[62:63]
	s_nop 0
	global_store_dword v[60:61], v56, off
	v_lshl_add_u64 v[62:63], v[70:71], 0, v[62:63]
	v_add_u32_e32 v56, s5, v87
	global_store_dword v[62:63], v57, off
	v_ashrrev_i32_e32 v57, 31, v56
	v_lshlrev_b64 v[56:57], 11, v[56:57]
	v_pk_mul_f32 v[32:33], v[64:65], v[32:33]
	v_lshl_add_u64 v[64:65], v[70:71], 0, v[56:57]
	v_add_u32_e32 v56, s5, v86
	v_ashrrev_i32_e32 v57, 31, v56
	v_lshlrev_b64 v[56:57], 11, v[56:57]
	v_pk_mul_f32 v[6:7], v[66:67], v[6:7]
	v_pk_mul_f32 v[14:15], v[66:67], v[14:15]
	v_pk_mul_f32 v[18:19], v[66:67], v[18:19]
	v_pk_mul_f32 v[22:23], v[66:67], v[22:23]
	v_pk_mul_f32 v[30:31], v[66:67], v[30:31]
	v_pk_mul_f32 v[34:35], v[66:67], v[34:35]
	v_lshl_add_u64 v[66:67], v[70:71], 0, v[56:57]
	global_store_dword v[64:65], v58, off
	global_store_dword v[66:67], v59, off
	ds_read_b128 v[56:59], v75 offset:4352
	s_waitcnt lgkmcnt(0)
	v_mfma_f32_16x16x32_bf16 v[48:51], v[48:51], v[56:59], 0
	ds_read_b128 v[56:59], v75 offset:4416
	s_add_i32 s50, s50, 32
	s_sub_i32 s51, s51, 32
	s_waitcnt lgkmcnt(0)
	v_mfma_f32_16x16x32_bf16 v[44:47], v[44:47], v[56:59], v[48:51]
	s_nop 0
	s_nop 1
	ds_read_b128 v[48:51], v75 offset:4480
	s_nop 0
	s_nop 0
	s_waitcnt lgkmcnt(0)
	v_mfma_f32_16x16x32_bf16 v[40:43], v[40:43], v[48:51], v[44:47]
	s_nop 2
	ds_read_b128 v[44:47], v75 offset:4544
	s_cmpk_eq_i32 s50, 0x8c0
	s_waitcnt lgkmcnt(0)
	v_mfma_f32_16x16x32_bf16 v[36:39], v[36:39], v[44:47], v[40:43]
	s_nop 2
	v_add_u32_e32 v40, 0x7000, v127
	ds_read2_b64 v[40:43], v40 offset0:32 offset1:36
	s_waitcnt lgkmcnt(0)
	v_mfma_f32_16x16x32_bf16 v[36:39], v[52:55], v[40:43], v[36:39]
	s_nop 7
	global_store_dword v[60:61], v36, off offset:64
	global_store_dword v[62:63], v37, off offset:64
	global_store_dword v[64:65], v38, off offset:64
	global_store_dword v[66:67], v39, off offset:64
	s_barrier
	s_waitcnt vmcnt(8)
	v_mov_b64_e32 v[84:85], v[214:215]
	v_mov_b64_e32 v[78:79], v[216:217]
	v_mov_b64_e32 v[82:83], v[218:219]
	v_mov_b64_e32 v[76:77], v[226:227]
	v_mov_b64_e32 v[0:1], v[220:221]
	v_mov_b64_e32 v[2:3], v[222:223]
	v_mov_b32_e32 v125, v206
	v_mov_b32_e32 v124, v207
	v_mov_b32_e32 v123, v208
	v_mov_b32_e32 v121, v209
	v_mov_b32_e32 v120, v211
	v_mov_b32_e32 v119, v212
	v_mov_b32_e32 v122, v210
	v_mov_b32_e32 v118, v213
	s_cbranch_scc1 .LBB0_928
	s_mov_b32 s61, s4
	v_mov_b32_e32 v36, v4
	v_mov_b32_e32 v37, v5
	v_mov_b32_e32 v38, v6
	v_mov_b32_e32 v39, v7
	v_mov_b32_e32 v40, v12
	v_mov_b32_e32 v41, v13
	v_mov_b32_e32 v42, v14
	v_mov_b32_e32 v43, v15
	v_mov_b32_e32 v44, v16
	v_mov_b32_e32 v45, v17
	v_mov_b32_e32 v46, v18
	v_mov_b32_e32 v47, v19
	v_mov_b32_e32 v48, v20
	v_mov_b32_e32 v49, v21
	v_mov_b32_e32 v50, v22
	v_mov_b32_e32 v51, v23
	v_mov_b32_e32 v52, v24
	v_mov_b32_e32 v53, v25
	v_mov_b32_e32 v54, v26
	v_mov_b32_e32 v55, v27
	v_mov_b32_e32 v56, v28
	v_mov_b32_e32 v57, v29
	v_mov_b32_e32 v58, v30
	v_mov_b32_e32 v59, v31
	v_mov_b32_e32 v60, v32
	v_mov_b32_e32 v61, v33
	v_mov_b32_e32 v62, v34
	v_mov_b32_e32 v63, v35
	v_mov_b32_e32 v64, v8
	v_mov_b32_e32 v65, v9
	v_mov_b32_e32 v66, v10
	v_mov_b32_e32 v67, v11
	s_branch .LBB0_908
